# st7 (MLP up) also on v_mfma_f32_16x16x32_bf16: K-loop, last K-tile, relu2 epilogue re-derived for the 16x16 accumulator layout (LDS-staged full-row stores)
# speedup vs baseline: 1.0376x; 1.0149x over previous
.LBB0_698:
	s_or_b64 exec, exec, s[14:15]
	s_waitcnt lgkmcnt(0)
	s_barrier
	v_and_b32_e32 v136, 15, v150
	v_bfe_u32 v137, v150, 4, 2
	v_lshrrev_b32_e32 v138, 6, v150
	v_lshrrev_b32_e32 v139, 8, v150
	v_and_b32_e32 v140, 7, v136
	v_lshrrev_b32_e32 v141, 1, v137
	v_and_b32_e32 v142, 1, v137
	v_lshlrev_b32_e32 v148, 7, v136
	v_lshl_add_u32 v148, v138, 13, v148
	v_add_u32_e32 v148, 0x10010, v148
	v_lshl_add_u32 v148, v142, 3, v148
	v_or_b32_e32 v149, 0, v141
	v_xor_b32_e32 v149, v149, v140
	v_lshl_add_u32 v144, v149, 4, v148
	v_or_b32_e32 v149, 2, v141
	v_xor_b32_e32 v149, v149, v140
	v_lshl_add_u32 v145, v149, 4, v148
	v_or_b32_e32 v149, 4, v141
	v_xor_b32_e32 v149, v149, v140
	v_lshl_add_u32 v146, v149, 4, v148
	v_or_b32_e32 v149, 6, v141
	v_xor_b32_e32 v149, v149, v140
	v_lshl_add_u32 v147, v149, 4, v148
	v_and_b32_e32 v140, 63, v150
	v_lshrrev_b32_e32 v141, 3, v140
	v_and_b32_e32 v142, 7, v140
	v_xor_b32_e32 v133, v141, v142
	v_lshlrev_b32_e32 v133, 4, v133
	v_lshl_add_u32 v133, v141, 7, v133
	v_lshl_add_u32 v133, v138, 13, v133
	v_add_u32_e32 v133, 0x10010, v133
	v_lshl_add_u32 v140, v139, 7, v141
	v_add_u32_e32 v134, s17, v140
	v_ashrrev_i32_e32 v135, 31, v134
	v_lshlrev_b64 v[134:135], 13, v[134:135]
	v_or_b32_e32 v140, s18, v163
	v_lshlrev_b32_e32 v140, 1, v140
	v_lshl_add_u32 v148, v142, 4, v140
	v_mov_b32_e32 v149, 0
	v_lshl_add_u64 v[134:135], s[8:9], 0, v[134:135]
	v_lshl_add_u64 v[134:135], v[134:135], 0, v[148:149]
	s_mov_b64 s[36:37], 0x10000
	v_lshl_add_u32 v149, v139, 7, v136
	v_lshlrev_b32_e32 v149, 2, v149
	v_add_u32_e32 v149, 0x20010, v149
	ds_read2_b32 v[136:137], v149 offset0:0 offset1:16
	ds_read2_b32 v[138:139], v149 offset0:32 offset1:48
	ds_read2_b32 v[140:141], v149 offset0:64 offset1:80
	ds_read2_b32 v[142:143], v149 offset0:96 offset1:112
	s_nop 7
	s_waitcnt lgkmcnt(0)
	v_mul_f32_e32 v0, v0, v136
	v_mul_f32_e32 v1, v1, v136
	v_mul_f32_e32 v2, v2, v136
	v_mul_f32_e32 v3, v3, v136
	v_max_f32_e32 v0, 0, v0
	v_max_f32_e32 v1, 0, v1
	v_max_f32_e32 v2, 0, v2
	v_max_f32_e32 v3, 0, v3
	v_mul_f32_e32 v0, v0, v0
	v_mul_f32_e32 v1, v1, v1
	v_mul_f32_e32 v2, v2, v2
	v_mul_f32_e32 v3, v3, v3
	v_cvt_pk_bf16_f32 v0, v0, v1
	v_cvt_pk_bf16_f32 v1, v2, v3
	ds_write_b64 v144, v[0:1]
	v_mul_f32_e32 v32, v32, v136
	v_mul_f32_e32 v33, v33, v136
	v_mul_f32_e32 v34, v34, v136
	v_mul_f32_e32 v35, v35, v136
	v_max_f32_e32 v32, 0, v32
	v_max_f32_e32 v33, 0, v33
	v_max_f32_e32 v34, 0, v34
	v_max_f32_e32 v35, 0, v35
	v_mul_f32_e32 v32, v32, v32
	v_mul_f32_e32 v33, v33, v33
	v_mul_f32_e32 v34, v34, v34
	v_mul_f32_e32 v35, v35, v35
	v_cvt_pk_bf16_f32 v32, v32, v33
	v_cvt_pk_bf16_f32 v33, v34, v35
	ds_write_b64 v145, v[32:33]
	v_mul_f32_e32 v64, v64, v136
	v_mul_f32_e32 v65, v65, v136
	v_mul_f32_e32 v66, v66, v136
	v_mul_f32_e32 v67, v67, v136
	v_max_f32_e32 v64, 0, v64
	v_max_f32_e32 v65, 0, v65
	v_max_f32_e32 v66, 0, v66
	v_max_f32_e32 v67, 0, v67
	v_mul_f32_e32 v64, v64, v64
	v_mul_f32_e32 v65, v65, v65
	v_mul_f32_e32 v66, v66, v66
	v_mul_f32_e32 v67, v67, v67
	v_cvt_pk_bf16_f32 v64, v64, v65
	v_cvt_pk_bf16_f32 v65, v66, v67
	ds_write_b64 v146, v[64:65]
	v_mul_f32_e32 v96, v96, v136
	v_mul_f32_e32 v97, v97, v136
	v_mul_f32_e32 v98, v98, v136
	v_mul_f32_e32 v99, v99, v136
	v_max_f32_e32 v96, 0, v96
	v_max_f32_e32 v97, 0, v97
	v_max_f32_e32 v98, 0, v98
	v_max_f32_e32 v99, 0, v99
	v_mul_f32_e32 v96, v96, v96
	v_mul_f32_e32 v97, v97, v97
	v_mul_f32_e32 v98, v98, v98
	v_mul_f32_e32 v99, v99, v99
	v_cvt_pk_bf16_f32 v96, v96, v97
	v_cvt_pk_bf16_f32 v97, v98, v99
	ds_write_b64 v147, v[96:97]
	v_mul_f32_e32 v4, v4, v137
	v_mul_f32_e32 v5, v5, v137
	v_mul_f32_e32 v6, v6, v137
	v_mul_f32_e32 v7, v7, v137
	v_max_f32_e32 v4, 0, v4
	v_max_f32_e32 v5, 0, v5
	v_max_f32_e32 v6, 0, v6
	v_max_f32_e32 v7, 0, v7
	v_mul_f32_e32 v4, v4, v4
	v_mul_f32_e32 v5, v5, v5
	v_mul_f32_e32 v6, v6, v6
	v_mul_f32_e32 v7, v7, v7
	v_cvt_pk_bf16_f32 v4, v4, v5
	v_cvt_pk_bf16_f32 v5, v6, v7
	ds_write_b64 v144, v[4:5] offset:2048
	v_mul_f32_e32 v36, v36, v137
	v_mul_f32_e32 v37, v37, v137
	v_mul_f32_e32 v38, v38, v137
	v_mul_f32_e32 v39, v39, v137
	v_max_f32_e32 v36, 0, v36
	v_max_f32_e32 v37, 0, v37
	v_max_f32_e32 v38, 0, v38
	v_max_f32_e32 v39, 0, v39
	v_mul_f32_e32 v36, v36, v36
	v_mul_f32_e32 v37, v37, v37
	v_mul_f32_e32 v38, v38, v38
	v_mul_f32_e32 v39, v39, v39
	v_cvt_pk_bf16_f32 v36, v36, v37
	v_cvt_pk_bf16_f32 v37, v38, v39
	ds_write_b64 v145, v[36:37] offset:2048
	v_mul_f32_e32 v68, v68, v137
	v_mul_f32_e32 v69, v69, v137
	v_mul_f32_e32 v70, v70, v137
	v_mul_f32_e32 v71, v71, v137
	v_max_f32_e32 v68, 0, v68
	v_max_f32_e32 v69, 0, v69
	v_max_f32_e32 v70, 0, v70
	v_max_f32_e32 v71, 0, v71
	v_mul_f32_e32 v68, v68, v68
	v_mul_f32_e32 v69, v69, v69
	v_mul_f32_e32 v70, v70, v70
	v_mul_f32_e32 v71, v71, v71
	v_cvt_pk_bf16_f32 v68, v68, v69
	v_cvt_pk_bf16_f32 v69, v70, v71
	ds_write_b64 v146, v[68:69] offset:2048
	v_mul_f32_e32 v100, v100, v137
	v_mul_f32_e32 v101, v101, v137
	v_mul_f32_e32 v102, v102, v137
	v_mul_f32_e32 v103, v103, v137
	v_max_f32_e32 v100, 0, v100
	v_max_f32_e32 v101, 0, v101
	v_max_f32_e32 v102, 0, v102
	v_max_f32_e32 v103, 0, v103
	v_mul_f32_e32 v100, v100, v100
	v_mul_f32_e32 v101, v101, v101
	v_mul_f32_e32 v102, v102, v102
	v_mul_f32_e32 v103, v103, v103
	v_cvt_pk_bf16_f32 v100, v100, v101
	v_cvt_pk_bf16_f32 v101, v102, v103
	ds_write_b64 v147, v[100:101] offset:2048
	v_mul_f32_e32 v8, v8, v138
	v_mul_f32_e32 v9, v9, v138
	v_mul_f32_e32 v10, v10, v138
	v_mul_f32_e32 v11, v11, v138
	v_max_f32_e32 v8, 0, v8
	v_max_f32_e32 v9, 0, v9
	v_max_f32_e32 v10, 0, v10
	v_max_f32_e32 v11, 0, v11
	v_mul_f32_e32 v8, v8, v8
	v_mul_f32_e32 v9, v9, v9
	v_mul_f32_e32 v10, v10, v10
	v_mul_f32_e32 v11, v11, v11
	v_cvt_pk_bf16_f32 v8, v8, v9
	v_cvt_pk_bf16_f32 v9, v10, v11
	ds_write_b64 v144, v[8:9] offset:4096
	v_mul_f32_e32 v40, v40, v138
	v_mul_f32_e32 v41, v41, v138
	v_mul_f32_e32 v42, v42, v138
	v_mul_f32_e32 v43, v43, v138
	v_max_f32_e32 v40, 0, v40
	v_max_f32_e32 v41, 0, v41
	v_max_f32_e32 v42, 0, v42
	v_max_f32_e32 v43, 0, v43
	v_mul_f32_e32 v40, v40, v40
	v_mul_f32_e32 v41, v41, v41
	v_mul_f32_e32 v42, v42, v42
	v_mul_f32_e32 v43, v43, v43
	v_cvt_pk_bf16_f32 v40, v40, v41
	v_cvt_pk_bf16_f32 v41, v42, v43
	ds_write_b64 v145, v[40:41] offset:4096
	v_mul_f32_e32 v72, v72, v138
	v_mul_f32_e32 v73, v73, v138
	v_mul_f32_e32 v74, v74, v138
	v_mul_f32_e32 v75, v75, v138
	v_max_f32_e32 v72, 0, v72
	v_max_f32_e32 v73, 0, v73
	v_max_f32_e32 v74, 0, v74
	v_max_f32_e32 v75, 0, v75
	v_mul_f32_e32 v72, v72, v72
	v_mul_f32_e32 v73, v73, v73
	v_mul_f32_e32 v74, v74, v74
	v_mul_f32_e32 v75, v75, v75
	v_cvt_pk_bf16_f32 v72, v72, v73
	v_cvt_pk_bf16_f32 v73, v74, v75
	ds_write_b64 v146, v[72:73] offset:4096
	v_mul_f32_e32 v104, v104, v138
	v_mul_f32_e32 v105, v105, v138
	v_mul_f32_e32 v106, v106, v138
	v_mul_f32_e32 v107, v107, v138
	v_max_f32_e32 v104, 0, v104
	v_max_f32_e32 v105, 0, v105
	v_max_f32_e32 v106, 0, v106
	v_max_f32_e32 v107, 0, v107
	v_mul_f32_e32 v104, v104, v104
	v_mul_f32_e32 v105, v105, v105
	v_mul_f32_e32 v106, v106, v106
	v_mul_f32_e32 v107, v107, v107
	v_cvt_pk_bf16_f32 v104, v104, v105
	v_cvt_pk_bf16_f32 v105, v106, v107
	ds_write_b64 v147, v[104:105] offset:4096
	v_mul_f32_e32 v12, v12, v139
	v_mul_f32_e32 v13, v13, v139
	v_mul_f32_e32 v14, v14, v139
	v_mul_f32_e32 v15, v15, v139
	v_max_f32_e32 v12, 0, v12
	v_max_f32_e32 v13, 0, v13
	v_max_f32_e32 v14, 0, v14
	v_max_f32_e32 v15, 0, v15
	v_mul_f32_e32 v12, v12, v12
	v_mul_f32_e32 v13, v13, v13
	v_mul_f32_e32 v14, v14, v14
	v_mul_f32_e32 v15, v15, v15
	v_cvt_pk_bf16_f32 v12, v12, v13
	v_cvt_pk_bf16_f32 v13, v14, v15
	ds_write_b64 v144, v[12:13] offset:6144
	v_mul_f32_e32 v44, v44, v139
	v_mul_f32_e32 v45, v45, v139
	v_mul_f32_e32 v46, v46, v139
	v_mul_f32_e32 v47, v47, v139
	v_max_f32_e32 v44, 0, v44
	v_max_f32_e32 v45, 0, v45
	v_max_f32_e32 v46, 0, v46
	v_max_f32_e32 v47, 0, v47
	v_mul_f32_e32 v44, v44, v44
	v_mul_f32_e32 v45, v45, v45
	v_mul_f32_e32 v46, v46, v46
	v_mul_f32_e32 v47, v47, v47
	v_cvt_pk_bf16_f32 v44, v44, v45
	v_cvt_pk_bf16_f32 v45, v46, v47
	ds_write_b64 v145, v[44:45] offset:6144
	v_mul_f32_e32 v76, v76, v139
	v_mul_f32_e32 v77, v77, v139
	v_mul_f32_e32 v78, v78, v139
	v_mul_f32_e32 v79, v79, v139
	v_max_f32_e32 v76, 0, v76
	v_max_f32_e32 v77, 0, v77
	v_max_f32_e32 v78, 0, v78
	v_max_f32_e32 v79, 0, v79
	v_mul_f32_e32 v76, v76, v76
	v_mul_f32_e32 v77, v77, v77
	v_mul_f32_e32 v78, v78, v78
	v_mul_f32_e32 v79, v79, v79
	v_cvt_pk_bf16_f32 v76, v76, v77
	v_cvt_pk_bf16_f32 v77, v78, v79
	ds_write_b64 v146, v[76:77] offset:6144
	v_mul_f32_e32 v108, v108, v139
	v_mul_f32_e32 v109, v109, v139
	v_mul_f32_e32 v110, v110, v139
	v_mul_f32_e32 v111, v111, v139
	v_max_f32_e32 v108, 0, v108
	v_max_f32_e32 v109, 0, v109
	v_max_f32_e32 v110, 0, v110
	v_max_f32_e32 v111, 0, v111
	v_mul_f32_e32 v108, v108, v108
	v_mul_f32_e32 v109, v109, v109
	v_mul_f32_e32 v110, v110, v110
	v_mul_f32_e32 v111, v111, v111
	v_cvt_pk_bf16_f32 v108, v108, v109
	v_cvt_pk_bf16_f32 v109, v110, v111
	ds_write_b64 v147, v[108:109] offset:6144
	s_waitcnt lgkmcnt(0)
	ds_read_b128 v[0:3], v133
	ds_read_b128 v[4:7], v133 offset:1024
	ds_read_b128 v[8:11], v133 offset:2048
	ds_read_b128 v[12:15], v133 offset:3072
	ds_read_b128 v[32:35], v133 offset:4096
	ds_read_b128 v[36:39], v133 offset:5120
	ds_read_b128 v[40:43], v133 offset:6144
	ds_read_b128 v[44:47], v133 offset:7168
	s_waitcnt lgkmcnt(7)
	global_store_dwordx4 v[134:135], v[0:3], off
	v_lshl_add_u64 v[134:135], v[134:135], 0, s[36:37]
	s_waitcnt lgkmcnt(6)
	global_store_dwordx4 v[134:135], v[4:7], off
	v_lshl_add_u64 v[134:135], v[134:135], 0, s[36:37]
	s_waitcnt lgkmcnt(5)
	global_store_dwordx4 v[134:135], v[8:11], off
	v_lshl_add_u64 v[134:135], v[134:135], 0, s[36:37]
	s_waitcnt lgkmcnt(4)
	global_store_dwordx4 v[134:135], v[12:15], off
	v_lshl_add_u64 v[134:135], v[134:135], 0, s[36:37]
	s_waitcnt lgkmcnt(3)
	global_store_dwordx4 v[134:135], v[32:35], off
	v_lshl_add_u64 v[134:135], v[134:135], 0, s[36:37]
	s_waitcnt lgkmcnt(2)
	global_store_dwordx4 v[134:135], v[36:39], off
	v_lshl_add_u64 v[134:135], v[134:135], 0, s[36:37]
	s_waitcnt lgkmcnt(1)
	global_store_dwordx4 v[134:135], v[40:43], off
	v_lshl_add_u64 v[134:135], v[134:135], 0, s[36:37]
	s_waitcnt lgkmcnt(0)
	global_store_dwordx4 v[134:135], v[44:47], off
	v_lshl_add_u64 v[134:135], v[134:135], 0, s[36:37]
	v_mul_f32_e32 v16, v16, v140
	v_mul_f32_e32 v17, v17, v140
	v_mul_f32_e32 v18, v18, v140
	v_mul_f32_e32 v19, v19, v140
	v_max_f32_e32 v16, 0, v16
	v_max_f32_e32 v17, 0, v17
	v_max_f32_e32 v18, 0, v18
	v_max_f32_e32 v19, 0, v19
	v_mul_f32_e32 v16, v16, v16
	v_mul_f32_e32 v17, v17, v17
	v_mul_f32_e32 v18, v18, v18
	v_mul_f32_e32 v19, v19, v19
	v_cvt_pk_bf16_f32 v16, v16, v17
	v_cvt_pk_bf16_f32 v17, v18, v19
	ds_write_b64 v144, v[16:17]
	v_mul_f32_e32 v48, v48, v140
	v_mul_f32_e32 v49, v49, v140
	v_mul_f32_e32 v50, v50, v140
	v_mul_f32_e32 v51, v51, v140
	v_max_f32_e32 v48, 0, v48
	v_max_f32_e32 v49, 0, v49
	v_max_f32_e32 v50, 0, v50
	v_max_f32_e32 v51, 0, v51
	v_mul_f32_e32 v48, v48, v48
	v_mul_f32_e32 v49, v49, v49
	v_mul_f32_e32 v50, v50, v50
	v_mul_f32_e32 v51, v51, v51
	v_cvt_pk_bf16_f32 v48, v48, v49
	v_cvt_pk_bf16_f32 v49, v50, v51
	ds_write_b64 v145, v[48:49]
	v_mul_f32_e32 v80, v80, v140
	v_mul_f32_e32 v81, v81, v140
	v_mul_f32_e32 v82, v82, v140
	v_mul_f32_e32 v83, v83, v140
	v_max_f32_e32 v80, 0, v80
	v_max_f32_e32 v81, 0, v81
	v_max_f32_e32 v82, 0, v82
	v_max_f32_e32 v83, 0, v83
	v_mul_f32_e32 v80, v80, v80
	v_mul_f32_e32 v81, v81, v81
	v_mul_f32_e32 v82, v82, v82
	v_mul_f32_e32 v83, v83, v83
	v_cvt_pk_bf16_f32 v80, v80, v81
	v_cvt_pk_bf16_f32 v81, v82, v83
	ds_write_b64 v146, v[80:81]
	v_mul_f32_e32 v112, v112, v140
	v_mul_f32_e32 v113, v113, v140
	v_mul_f32_e32 v114, v114, v140
	v_mul_f32_e32 v115, v115, v140
	v_max_f32_e32 v112, 0, v112
	v_max_f32_e32 v113, 0, v113
	v_max_f32_e32 v114, 0, v114
	v_max_f32_e32 v115, 0, v115
	v_mul_f32_e32 v112, v112, v112
	v_mul_f32_e32 v113, v113, v113
	v_mul_f32_e32 v114, v114, v114
	v_mul_f32_e32 v115, v115, v115
	v_cvt_pk_bf16_f32 v112, v112, v113
	v_cvt_pk_bf16_f32 v113, v114, v115
	ds_write_b64 v147, v[112:113]
	v_mul_f32_e32 v20, v20, v141
	v_mul_f32_e32 v21, v21, v141
	v_mul_f32_e32 v22, v22, v141
	v_mul_f32_e32 v23, v23, v141
	v_max_f32_e32 v20, 0, v20
	v_max_f32_e32 v21, 0, v21
	v_max_f32_e32 v22, 0, v22
	v_max_f32_e32 v23, 0, v23
	v_mul_f32_e32 v20, v20, v20
	v_mul_f32_e32 v21, v21, v21
	v_mul_f32_e32 v22, v22, v22
	v_mul_f32_e32 v23, v23, v23
	v_cvt_pk_bf16_f32 v20, v20, v21
	v_cvt_pk_bf16_f32 v21, v22, v23
	ds_write_b64 v144, v[20:21] offset:2048
	v_mul_f32_e32 v52, v52, v141
	v_mul_f32_e32 v53, v53, v141
	v_mul_f32_e32 v54, v54, v141
	v_mul_f32_e32 v55, v55, v141
	v_max_f32_e32 v52, 0, v52
	v_max_f32_e32 v53, 0, v53
	v_max_f32_e32 v54, 0, v54
	v_max_f32_e32 v55, 0, v55
	v_mul_f32_e32 v52, v52, v52
	v_mul_f32_e32 v53, v53, v53
	v_mul_f32_e32 v54, v54, v54
	v_mul_f32_e32 v55, v55, v55
	v_cvt_pk_bf16_f32 v52, v52, v53
	v_cvt_pk_bf16_f32 v53, v54, v55
	ds_write_b64 v145, v[52:53] offset:2048
	v_mul_f32_e32 v84, v84, v141
	v_mul_f32_e32 v85, v85, v141
	v_mul_f32_e32 v86, v86, v141
	v_mul_f32_e32 v87, v87, v141
	v_max_f32_e32 v84, 0, v84
	v_max_f32_e32 v85, 0, v85
	v_max_f32_e32 v86, 0, v86
	v_max_f32_e32 v87, 0, v87
	v_mul_f32_e32 v84, v84, v84
	v_mul_f32_e32 v85, v85, v85
	v_mul_f32_e32 v86, v86, v86
	v_mul_f32_e32 v87, v87, v87
	v_cvt_pk_bf16_f32 v84, v84, v85
	v_cvt_pk_bf16_f32 v85, v86, v87
	ds_write_b64 v146, v[84:85] offset:2048
	v_mul_f32_e32 v116, v116, v141
	v_mul_f32_e32 v117, v117, v141
	v_mul_f32_e32 v118, v118, v141
	v_mul_f32_e32 v119, v119, v141
	v_max_f32_e32 v116, 0, v116
	v_max_f32_e32 v117, 0, v117
	v_max_f32_e32 v118, 0, v118
	v_max_f32_e32 v119, 0, v119
	v_mul_f32_e32 v116, v116, v116
	v_mul_f32_e32 v117, v117, v117
	v_mul_f32_e32 v118, v118, v118
	v_mul_f32_e32 v119, v119, v119
	v_cvt_pk_bf16_f32 v116, v116, v117
	v_cvt_pk_bf16_f32 v117, v118, v119
	ds_write_b64 v147, v[116:117] offset:2048
	v_mul_f32_e32 v24, v24, v142
	v_mul_f32_e32 v25, v25, v142
	v_mul_f32_e32 v26, v26, v142
	v_mul_f32_e32 v27, v27, v142
	v_max_f32_e32 v24, 0, v24
	v_max_f32_e32 v25, 0, v25
	v_max_f32_e32 v26, 0, v26
	v_max_f32_e32 v27, 0, v27
	v_mul_f32_e32 v24, v24, v24
	v_mul_f32_e32 v25, v25, v25
	v_mul_f32_e32 v26, v26, v26
	v_mul_f32_e32 v27, v27, v27
	v_cvt_pk_bf16_f32 v24, v24, v25
	v_cvt_pk_bf16_f32 v25, v26, v27
	ds_write_b64 v144, v[24:25] offset:4096
	v_mul_f32_e32 v56, v56, v142
	v_mul_f32_e32 v57, v57, v142
	v_mul_f32_e32 v58, v58, v142
	v_mul_f32_e32 v59, v59, v142
	v_max_f32_e32 v56, 0, v56
	v_max_f32_e32 v57, 0, v57
	v_max_f32_e32 v58, 0, v58
	v_max_f32_e32 v59, 0, v59
	v_mul_f32_e32 v56, v56, v56
	v_mul_f32_e32 v57, v57, v57
	v_mul_f32_e32 v58, v58, v58
	v_mul_f32_e32 v59, v59, v59
	v_cvt_pk_bf16_f32 v56, v56, v57
	v_cvt_pk_bf16_f32 v57, v58, v59
	ds_write_b64 v145, v[56:57] offset:4096
	v_mul_f32_e32 v88, v88, v142
	v_mul_f32_e32 v89, v89, v142
	v_mul_f32_e32 v90, v90, v142
	v_mul_f32_e32 v91, v91, v142
	v_max_f32_e32 v88, 0, v88
	v_max_f32_e32 v89, 0, v89
	v_max_f32_e32 v90, 0, v90
	v_max_f32_e32 v91, 0, v91
	v_mul_f32_e32 v88, v88, v88
	v_mul_f32_e32 v89, v89, v89
	v_mul_f32_e32 v90, v90, v90
	v_mul_f32_e32 v91, v91, v91
	v_cvt_pk_bf16_f32 v88, v88, v89
	v_cvt_pk_bf16_f32 v89, v90, v91
	ds_write_b64 v146, v[88:89] offset:4096
	v_mul_f32_e32 v120, v120, v142
	v_mul_f32_e32 v121, v121, v142
	v_mul_f32_e32 v122, v122, v142
	v_mul_f32_e32 v123, v123, v142
	v_max_f32_e32 v120, 0, v120
	v_max_f32_e32 v121, 0, v121
	v_max_f32_e32 v122, 0, v122
	v_max_f32_e32 v123, 0, v123
	v_mul_f32_e32 v120, v120, v120
	v_mul_f32_e32 v121, v121, v121
	v_mul_f32_e32 v122, v122, v122
	v_mul_f32_e32 v123, v123, v123
	v_cvt_pk_bf16_f32 v120, v120, v121
	v_cvt_pk_bf16_f32 v121, v122, v123
	ds_write_b64 v147, v[120:121] offset:4096
	v_mul_f32_e32 v28, v28, v143
	v_mul_f32_e32 v29, v29, v143
	v_mul_f32_e32 v30, v30, v143
	v_mul_f32_e32 v31, v31, v143
	v_max_f32_e32 v28, 0, v28
	v_max_f32_e32 v29, 0, v29
	v_max_f32_e32 v30, 0, v30
	v_max_f32_e32 v31, 0, v31
	v_mul_f32_e32 v28, v28, v28
	v_mul_f32_e32 v29, v29, v29
	v_mul_f32_e32 v30, v30, v30
	v_mul_f32_e32 v31, v31, v31
	v_cvt_pk_bf16_f32 v28, v28, v29
	v_cvt_pk_bf16_f32 v29, v30, v31
	ds_write_b64 v144, v[28:29] offset:6144
	v_mul_f32_e32 v60, v60, v143
	v_mul_f32_e32 v61, v61, v143
	v_mul_f32_e32 v62, v62, v143
	v_mul_f32_e32 v63, v63, v143
	v_max_f32_e32 v60, 0, v60
	v_max_f32_e32 v61, 0, v61
	v_max_f32_e32 v62, 0, v62
	v_max_f32_e32 v63, 0, v63
	v_mul_f32_e32 v60, v60, v60
	v_mul_f32_e32 v61, v61, v61
	v_mul_f32_e32 v62, v62, v62
	v_mul_f32_e32 v63, v63, v63
	v_cvt_pk_bf16_f32 v60, v60, v61
	v_cvt_pk_bf16_f32 v61, v62, v63
	ds_write_b64 v145, v[60:61] offset:6144
	v_mul_f32_e32 v92, v92, v143
	v_mul_f32_e32 v93, v93, v143
	v_mul_f32_e32 v94, v94, v143
	v_mul_f32_e32 v95, v95, v143
	v_max_f32_e32 v92, 0, v92
	v_max_f32_e32 v93, 0, v93
	v_max_f32_e32 v94, 0, v94
	v_max_f32_e32 v95, 0, v95
	v_mul_f32_e32 v92, v92, v92
	v_mul_f32_e32 v93, v93, v93
	v_mul_f32_e32 v94, v94, v94
	v_mul_f32_e32 v95, v95, v95
	v_cvt_pk_bf16_f32 v92, v92, v93
	v_cvt_pk_bf16_f32 v93, v94, v95
	ds_write_b64 v146, v[92:93] offset:6144
	v_mul_f32_e32 v124, v124, v143
	v_mul_f32_e32 v125, v125, v143
	v_mul_f32_e32 v126, v126, v143
	v_mul_f32_e32 v127, v127, v143
	v_max_f32_e32 v124, 0, v124
	v_max_f32_e32 v125, 0, v125
	v_max_f32_e32 v126, 0, v126
	v_max_f32_e32 v127, 0, v127
	v_mul_f32_e32 v124, v124, v124
	v_mul_f32_e32 v125, v125, v125
	v_mul_f32_e32 v126, v126, v126
	v_mul_f32_e32 v127, v127, v127
	v_cvt_pk_bf16_f32 v124, v124, v125
	v_cvt_pk_bf16_f32 v125, v126, v127
	ds_write_b64 v147, v[124:125] offset:6144
	s_waitcnt lgkmcnt(0)
	ds_read_b128 v[16:19], v133
	ds_read_b128 v[20:23], v133 offset:1024
	ds_read_b128 v[24:27], v133 offset:2048
	ds_read_b128 v[28:31], v133 offset:3072
	ds_read_b128 v[48:51], v133 offset:4096
	ds_read_b128 v[52:55], v133 offset:5120
	ds_read_b128 v[56:59], v133 offset:6144
	ds_read_b128 v[60:63], v133 offset:7168
	s_waitcnt lgkmcnt(7)
	global_store_dwordx4 v[134:135], v[16:19], off
	v_lshl_add_u64 v[134:135], v[134:135], 0, s[36:37]
	s_waitcnt lgkmcnt(6)
	global_store_dwordx4 v[134:135], v[20:23], off
	v_lshl_add_u64 v[134:135], v[134:135], 0, s[36:37]
	s_waitcnt lgkmcnt(5)
	global_store_dwordx4 v[134:135], v[24:27], off
	v_lshl_add_u64 v[134:135], v[134:135], 0, s[36:37]
	s_waitcnt lgkmcnt(4)
	global_store_dwordx4 v[134:135], v[28:31], off
	v_lshl_add_u64 v[134:135], v[134:135], 0, s[36:37]
	s_waitcnt lgkmcnt(3)
	global_store_dwordx4 v[134:135], v[48:51], off
	v_lshl_add_u64 v[134:135], v[134:135], 0, s[36:37]
	s_waitcnt lgkmcnt(2)
	global_store_dwordx4 v[134:135], v[52:55], off
	v_lshl_add_u64 v[134:135], v[134:135], 0, s[36:37]
	s_waitcnt lgkmcnt(1)
	global_store_dwordx4 v[134:135], v[56:59], off
	v_lshl_add_u64 v[134:135], v[134:135], 0, s[36:37]
	s_waitcnt lgkmcnt(0)
	global_store_dwordx4 v[134:135], v[60:63], off
	v_lshl_add_u64 v[134:135], v[134:135], 0, s[36:37]
	s_and_b64 vcc, exec, s[2:3]
	s_waitcnt vmcnt(63) expcnt(7) lgkmcnt(15)
	s_barrier
	s_cbranch_vccnz .LBB0_709

.LBB0_701:
	v_lshl_add_u64 v[148:149], v[0:1], 0, s[66:67]
	v_mov_b32_e32 v0, 0
	v_lshl_add_u64 v[134:135], v[14:15], 0, s[66:67]
	v_lshl_add_u64 v[136:137], v[12:13], 0, s[66:67]
	v_lshl_add_u64 v[138:139], v[10:11], 0, s[66:67]
	v_lshl_add_u64 v[140:141], v[8:9], 0, s[66:67]
	v_lshl_add_u64 v[142:143], v[6:7], 0, s[66:67]
	v_lshl_add_u64 v[144:145], v[4:5], 0, s[66:67]
	v_lshl_add_u64 v[146:147], v[2:3], 0, s[66:67]
	s_mov_b32 s0, 0
	s_mov_b64 s[2:3], 0
	v_mov_b32_e32 v1, v0
	v_mov_b32_e32 v2, v0
	v_mov_b32_e32 v3, v0
	v_mov_b32_e32 v4, v0
	v_mov_b32_e32 v5, v0
	v_mov_b32_e32 v6, v0
	v_mov_b32_e32 v7, v0
	v_mov_b32_e32 v8, v0
	v_mov_b32_e32 v9, v0
	v_mov_b32_e32 v10, v0
	v_mov_b32_e32 v11, v0
	v_mov_b32_e32 v12, v0
	v_mov_b32_e32 v13, v0
	v_mov_b32_e32 v14, v0
	v_mov_b32_e32 v15, v0
	v_mov_b32_e32 v32, v0
	v_mov_b32_e32 v33, v0
	v_mov_b32_e32 v34, v0
	v_mov_b32_e32 v35, v0
	v_mov_b32_e32 v36, v0
	v_mov_b32_e32 v37, v0
	v_mov_b32_e32 v38, v0
	v_mov_b32_e32 v39, v0
	v_mov_b32_e32 v40, v0
	v_mov_b32_e32 v41, v0
	v_mov_b32_e32 v42, v0
	v_mov_b32_e32 v43, v0
	v_mov_b32_e32 v44, v0
	v_mov_b32_e32 v45, v0
	v_mov_b32_e32 v46, v0
	v_mov_b32_e32 v47, v0
	v_mov_b32_e32 v64, v0
	v_mov_b32_e32 v65, v0
	v_mov_b32_e32 v66, v0
	v_mov_b32_e32 v67, v0
	v_mov_b32_e32 v68, v0
	v_mov_b32_e32 v69, v0
	v_mov_b32_e32 v70, v0
	v_mov_b32_e32 v71, v0
	v_mov_b32_e32 v72, v0
	v_mov_b32_e32 v73, v0
	v_mov_b32_e32 v74, v0
	v_mov_b32_e32 v75, v0
	v_mov_b32_e32 v76, v0
	v_mov_b32_e32 v77, v0
	v_mov_b32_e32 v78, v0
	v_mov_b32_e32 v79, v0
	v_mov_b32_e32 v96, v0
	v_mov_b32_e32 v97, v0
	v_mov_b32_e32 v98, v0
	v_mov_b32_e32 v99, v0
	v_mov_b32_e32 v100, v0
	v_mov_b32_e32 v101, v0
	v_mov_b32_e32 v102, v0
	v_mov_b32_e32 v103, v0
	v_mov_b32_e32 v104, v0
	v_mov_b32_e32 v105, v0
	v_mov_b32_e32 v106, v0
	v_mov_b32_e32 v107, v0
	v_mov_b32_e32 v108, v0
	v_mov_b32_e32 v109, v0
	v_mov_b32_e32 v110, v0
	v_mov_b32_e32 v111, v0
	v_mov_b32_e32 v16, v0
	v_mov_b32_e32 v17, v0
	v_mov_b32_e32 v18, v0
	v_mov_b32_e32 v19, v0
	v_mov_b32_e32 v20, v0
	v_mov_b32_e32 v21, v0
	v_mov_b32_e32 v22, v0
	v_mov_b32_e32 v23, v0
	v_mov_b32_e32 v24, v0
	v_mov_b32_e32 v25, v0
	v_mov_b32_e32 v26, v0
	v_mov_b32_e32 v27, v0
	v_mov_b32_e32 v28, v0
	v_mov_b32_e32 v29, v0
	v_mov_b32_e32 v30, v0
	v_mov_b32_e32 v31, v0
	v_mov_b32_e32 v48, v0
	v_mov_b32_e32 v49, v0
	v_mov_b32_e32 v50, v0
	v_mov_b32_e32 v51, v0
	v_mov_b32_e32 v52, v0
	v_mov_b32_e32 v53, v0
	v_mov_b32_e32 v54, v0
	v_mov_b32_e32 v55, v0
	v_mov_b32_e32 v56, v0
	v_mov_b32_e32 v57, v0
	v_mov_b32_e32 v58, v0
	v_mov_b32_e32 v59, v0
	v_mov_b32_e32 v60, v0
	v_mov_b32_e32 v61, v0
	v_mov_b32_e32 v62, v0
	v_mov_b32_e32 v63, v0
	v_mov_b32_e32 v80, v0
	v_mov_b32_e32 v81, v0
	v_mov_b32_e32 v82, v0
	v_mov_b32_e32 v83, v0
	v_mov_b32_e32 v84, v0
	v_mov_b32_e32 v85, v0
	v_mov_b32_e32 v86, v0
	v_mov_b32_e32 v87, v0
	v_mov_b32_e32 v88, v0
	v_mov_b32_e32 v89, v0
	v_mov_b32_e32 v90, v0
	v_mov_b32_e32 v91, v0
	v_mov_b32_e32 v92, v0
	v_mov_b32_e32 v93, v0
	v_mov_b32_e32 v94, v0
	v_mov_b32_e32 v95, v0
	v_mov_b32_e32 v112, v0
	v_mov_b32_e32 v113, v0
	v_mov_b32_e32 v114, v0
	v_mov_b32_e32 v115, v0
	v_mov_b32_e32 v116, v0
	v_mov_b32_e32 v117, v0
	v_mov_b32_e32 v118, v0
	v_mov_b32_e32 v119, v0
	v_mov_b32_e32 v120, v0
	v_mov_b32_e32 v121, v0
	v_mov_b32_e32 v122, v0
	v_mov_b32_e32 v123, v0
	v_mov_b32_e32 v124, v0
	v_mov_b32_e32 v125, v0
	v_mov_b32_e32 v126, v0
	v_mov_b32_e32 v127, v0
	v_and_b32_e32 v238, 15, v184
	v_bfe_u32 v239, v184, 4, 2
	v_bfe_u32 v240, v184, 1, 3
	v_xor_b32_e32 v239, v239, v240
	v_lshlrev_b32_e32 v239, 4, v239
	v_lshl_add_u32 v239, v238, 7, v239
	v_lshrrev_b32_e32 v240, 8, v184
	v_lshl_add_u32 v236, v240, 14, v239
	v_bfe_u32 v240, v184, 6, 2
	v_lshl_add_u32 v237, v240, 13, v239
	v_add_u32_e32 v237, 0x8000, v237
.LBB0_702:
	s_add_i32 s1, s0, 0x10000
	s_and_b32 s14, s1, 0x10000
	s_and_b32 s0, s0, 0x10000
	s_add_i32 s0, s0, 16
	v_add_u32_e32 v190, s14, v161
	s_nop 0
	v_readfirstlane_b32 s14, v190
	s_waitcnt vmcnt(0)
	s_barrier
	v_add_u32_e32 v239, s0, v237
	ds_read_b128 v[202:205], v239
	ds_read_b128 v[206:209], v239 offset:2048
	ds_read_b128 v[210:213], v239 offset:4096
	ds_read_b128 v[214:217], v239 offset:6144
	v_add_u32_e32 v238, s0, v236
	ds_read_b128 v[218:221], v238
	ds_read_b128 v[178:181], v238 offset:2048
	ds_read_b128 v[222:225], v238 offset:4096
	ds_read_b128 v[226:229], v238 offset:6144
	v_lshl_add_u64 v[230:231], v[148:149], 0, s[2:3]
	s_mov_b32 m0, s14
	s_nop 0
	global_load_lds_dwordx4 v[230:231], off
	s_waitcnt lgkmcnt(3)
	v_mfma_f32_16x16x32_bf16 v[0:3], v[202:205], v[218:221], v[0:3]
	v_mfma_f32_16x16x32_bf16 v[32:35], v[206:209], v[218:221], v[32:35]
	v_lshl_add_u64 v[230:231], v[146:147], 0, s[2:3]
	s_add_i32 s15, s14, 0x2000
	s_mov_b32 m0, s15
	s_nop 0
	global_load_lds_dwordx4 v[230:231], off
	v_mfma_f32_16x16x32_bf16 v[64:67], v[210:213], v[218:221], v[64:67]
	v_mfma_f32_16x16x32_bf16 v[96:99], v[214:217], v[218:221], v[96:99]
	s_waitcnt lgkmcnt(2)
	v_mfma_f32_16x16x32_bf16 v[4:7], v[202:205], v[178:181], v[4:7]
	v_mfma_f32_16x16x32_bf16 v[36:39], v[206:209], v[178:181], v[36:39]
	v_lshl_add_u64 v[230:231], v[144:145], 0, s[2:3]
	s_add_i32 s15, s14, 0x4000
	s_mov_b32 m0, s15
	s_nop 0
	global_load_lds_dwordx4 v[230:231], off
	v_mfma_f32_16x16x32_bf16 v[68:71], v[210:213], v[178:181], v[68:71]
	v_mfma_f32_16x16x32_bf16 v[100:103], v[214:217], v[178:181], v[100:103]
	s_waitcnt lgkmcnt(1)
	v_mfma_f32_16x16x32_bf16 v[8:11], v[202:205], v[222:225], v[8:11]
	v_mfma_f32_16x16x32_bf16 v[40:43], v[206:209], v[222:225], v[40:43]
	v_lshl_add_u64 v[230:231], v[142:143], 0, s[2:3]
	s_add_i32 s15, s14, 0x6000
	s_mov_b32 m0, s15
	s_nop 0
	global_load_lds_dwordx4 v[230:231], off
	v_mfma_f32_16x16x32_bf16 v[72:75], v[210:213], v[222:225], v[72:75]
	v_mfma_f32_16x16x32_bf16 v[104:107], v[214:217], v[222:225], v[104:107]
	s_waitcnt lgkmcnt(0)
	v_mfma_f32_16x16x32_bf16 v[12:15], v[202:205], v[226:229], v[12:15]
	v_mfma_f32_16x16x32_bf16 v[44:47], v[206:209], v[226:229], v[44:47]
	v_lshl_add_u64 v[230:231], v[140:141], 0, s[2:3]
	s_add_i32 s15, s14, 0x8000
	s_mov_b32 m0, s15
	s_nop 0
	global_load_lds_dwordx4 v[230:231], off
	v_mfma_f32_16x16x32_bf16 v[76:79], v[210:213], v[226:229], v[76:79]
	v_mfma_f32_16x16x32_bf16 v[108:111], v[214:217], v[226:229], v[108:111]
	ds_read_b128 v[218:221], v238 offset:8192
	ds_read_b128 v[178:181], v238 offset:10240
	ds_read_b128 v[222:225], v238 offset:12288
	ds_read_b128 v[226:229], v238 offset:14336
	s_waitcnt lgkmcnt(3)
	v_mfma_f32_16x16x32_bf16 v[16:19], v[202:205], v[218:221], v[16:19]
	v_mfma_f32_16x16x32_bf16 v[48:51], v[206:209], v[218:221], v[48:51]
	v_lshl_add_u64 v[230:231], v[138:139], 0, s[2:3]
	s_add_i32 s15, s14, 0xa000
	s_mov_b32 m0, s15
	s_nop 0
	global_load_lds_dwordx4 v[230:231], off
	v_mfma_f32_16x16x32_bf16 v[80:83], v[210:213], v[218:221], v[80:83]
	v_mfma_f32_16x16x32_bf16 v[112:115], v[214:217], v[218:221], v[112:115]
	s_waitcnt lgkmcnt(2)
	v_mfma_f32_16x16x32_bf16 v[20:23], v[202:205], v[178:181], v[20:23]
	v_mfma_f32_16x16x32_bf16 v[52:55], v[206:209], v[178:181], v[52:55]
	v_lshl_add_u64 v[230:231], v[136:137], 0, s[2:3]
	s_add_i32 s15, s14, 0xc000
	s_mov_b32 m0, s15
	s_nop 0
	global_load_lds_dwordx4 v[230:231], off
	v_mfma_f32_16x16x32_bf16 v[84:87], v[210:213], v[178:181], v[84:87]
	v_mfma_f32_16x16x32_bf16 v[116:119], v[214:217], v[178:181], v[116:119]
	s_waitcnt lgkmcnt(1)
	v_mfma_f32_16x16x32_bf16 v[24:27], v[202:205], v[222:225], v[24:27]
	v_mfma_f32_16x16x32_bf16 v[56:59], v[206:209], v[222:225], v[56:59]
	v_lshl_add_u64 v[230:231], v[134:135], 0, s[2:3]
	s_add_i32 s15, s14, 0xe000
	s_mov_b32 m0, s15
	s_nop 0
	global_load_lds_dwordx4 v[230:231], off
	s_add_u32 s2, s2, 0x80
	s_addc_u32 s3, s3, 0
	s_cmpk_eq_i32 s2, 0x780
	v_mfma_f32_16x16x32_bf16 v[88:91], v[210:213], v[222:225], v[88:91]
	v_mfma_f32_16x16x32_bf16 v[120:123], v[214:217], v[222:225], v[120:123]
	s_waitcnt lgkmcnt(0)
	v_mfma_f32_16x16x32_bf16 v[28:31], v[202:205], v[226:229], v[28:31]
	v_mfma_f32_16x16x32_bf16 v[60:63], v[206:209], v[226:229], v[60:63]
	v_mfma_f32_16x16x32_bf16 v[92:95], v[210:213], v[226:229], v[92:95]
	v_mfma_f32_16x16x32_bf16 v[124:127], v[214:217], v[226:229], v[124:127]
	v_xor_b32_e32 v239, 64, v237
	v_add_u32_e32 v239, s0, v239
	ds_read_b128 v[202:205], v239
	ds_read_b128 v[206:209], v239 offset:2048
	ds_read_b128 v[210:213], v239 offset:4096
	ds_read_b128 v[214:217], v239 offset:6144
	v_xor_b32_e32 v238, 64, v236
	v_add_u32_e32 v238, s0, v238
	ds_read_b128 v[218:221], v238
	ds_read_b128 v[178:181], v238 offset:2048
	ds_read_b128 v[222:225], v238 offset:4096
	ds_read_b128 v[226:229], v238 offset:6144
	s_waitcnt lgkmcnt(3)
	v_mfma_f32_16x16x32_bf16 v[0:3], v[202:205], v[218:221], v[0:3]
	v_mfma_f32_16x16x32_bf16 v[32:35], v[206:209], v[218:221], v[32:35]
	v_mfma_f32_16x16x32_bf16 v[64:67], v[210:213], v[218:221], v[64:67]
	v_mfma_f32_16x16x32_bf16 v[96:99], v[214:217], v[218:221], v[96:99]
	s_waitcnt lgkmcnt(2)
	v_mfma_f32_16x16x32_bf16 v[4:7], v[202:205], v[178:181], v[4:7]
	v_mfma_f32_16x16x32_bf16 v[36:39], v[206:209], v[178:181], v[36:39]
	v_mfma_f32_16x16x32_bf16 v[68:71], v[210:213], v[178:181], v[68:71]
	v_mfma_f32_16x16x32_bf16 v[100:103], v[214:217], v[178:181], v[100:103]
	s_waitcnt lgkmcnt(1)
	v_mfma_f32_16x16x32_bf16 v[8:11], v[202:205], v[222:225], v[8:11]
	v_mfma_f32_16x16x32_bf16 v[40:43], v[206:209], v[222:225], v[40:43]
	v_mfma_f32_16x16x32_bf16 v[72:75], v[210:213], v[222:225], v[72:75]
	v_mfma_f32_16x16x32_bf16 v[104:107], v[214:217], v[222:225], v[104:107]
	s_waitcnt lgkmcnt(0)
	v_mfma_f32_16x16x32_bf16 v[12:15], v[202:205], v[226:229], v[12:15]
	v_mfma_f32_16x16x32_bf16 v[44:47], v[206:209], v[226:229], v[44:47]
	v_mfma_f32_16x16x32_bf16 v[76:79], v[210:213], v[226:229], v[76:79]
	v_mfma_f32_16x16x32_bf16 v[108:111], v[214:217], v[226:229], v[108:111]
	ds_read_b128 v[218:221], v238 offset:8192
	ds_read_b128 v[178:181], v238 offset:10240
	ds_read_b128 v[222:225], v238 offset:12288
	ds_read_b128 v[226:229], v238 offset:14336
	s_waitcnt lgkmcnt(3)
	v_mfma_f32_16x16x32_bf16 v[16:19], v[202:205], v[218:221], v[16:19]
	v_mfma_f32_16x16x32_bf16 v[48:51], v[206:209], v[218:221], v[48:51]
	v_mfma_f32_16x16x32_bf16 v[80:83], v[210:213], v[218:221], v[80:83]
	v_mfma_f32_16x16x32_bf16 v[112:115], v[214:217], v[218:221], v[112:115]
	s_waitcnt lgkmcnt(2)
	v_mfma_f32_16x16x32_bf16 v[20:23], v[202:205], v[178:181], v[20:23]
	v_mfma_f32_16x16x32_bf16 v[52:55], v[206:209], v[178:181], v[52:55]
	v_mfma_f32_16x16x32_bf16 v[84:87], v[210:213], v[178:181], v[84:87]
	v_mfma_f32_16x16x32_bf16 v[116:119], v[214:217], v[178:181], v[116:119]
	s_waitcnt lgkmcnt(1)
	v_mfma_f32_16x16x32_bf16 v[24:27], v[202:205], v[222:225], v[24:27]
	v_mfma_f32_16x16x32_bf16 v[56:59], v[206:209], v[222:225], v[56:59]
	v_mfma_f32_16x16x32_bf16 v[88:91], v[210:213], v[222:225], v[88:91]
	v_mfma_f32_16x16x32_bf16 v[120:123], v[214:217], v[222:225], v[120:123]
	s_waitcnt lgkmcnt(0)
	v_mfma_f32_16x16x32_bf16 v[28:31], v[202:205], v[226:229], v[28:31]
	v_mfma_f32_16x16x32_bf16 v[60:63], v[206:209], v[226:229], v[60:63]
	v_mfma_f32_16x16x32_bf16 v[92:95], v[210:213], v[226:229], v[92:95]
	v_mfma_f32_16x16x32_bf16 v[124:127], v[214:217], v[226:229], v[124:127]
	s_mov_b32 s0, s1
	s_cbranch_scc0 .LBB0_702
	s_waitcnt vmcnt(0)
	s_barrier
	v_mov_b32_e32 v133, 0x358637bd
	s_and_saveexec_b64 s[2:3], s[6:7]
	s_cbranch_execz .LBB0_705
	v_add_u32_e32 v134, s17, v150
	v_ashrrev_i32_e32 v135, 31, v134
	v_lshlrev_b64 v[134:135], 6, v[134:135]
	v_lshl_add_u64 v[146:147], s[10:11], 0, v[134:135]
	global_load_dwordx4 v[134:137], v[146:147], off
	global_load_dwordx4 v[138:141], v[146:147], off offset:16
	global_load_dwordx4 v[142:145], v[146:147], off offset:32
	s_nop 0
	global_load_dwordx4 v[146:149], v[146:147], off offset:48
	s_waitcnt vmcnt(3)
	v_mov_b32_e32 v178, v135
	v_mov_b32_e32 v179, v136
	v_mov_b32_e32 v135, v137
	v_pk_add_f32 v[134:135], v[178:179], v[134:135]
	s_waitcnt vmcnt(2)
	v_mov_b32_e32 v180, v139
	v_mov_b32_e32 v181, v140
	v_mov_b32_e32 v139, v141
	v_add_f32_e32 v133, 0, v134
	v_pk_add_f32 v[136:137], v[180:181], v[138:139]
	v_add_f32_e32 v133, v133, v135
	s_waitcnt vmcnt(1)
	v_mov_b32_e32 v182, v143
	v_mov_b32_e32 v183, v144
	v_mov_b32_e32 v143, v145
	v_add_f32_e32 v133, v133, v136
	v_pk_add_f32 v[138:139], v[182:183], v[142:143]
	v_add_f32_e32 v133, v133, v137
	s_waitcnt vmcnt(0)
	v_mov_b32_e32 v202, v147
	v_mov_b32_e32 v203, v148
	v_mov_b32_e32 v147, v149
	v_add_f32_e32 v133, v133, v138
	v_add_f32_e32 v133, v133, v139
	v_pk_add_f32 v[134:135], v[202:203], v[146:147]
	s_nop 0
	v_add_f32_e32 v133, v133, v134
	v_add_f32_e32 v133, v133, v135
	v_fmamk_f32 v133, v133, 0x3a800000, v187

.LBB0_707:
	v_add_u32_e32 v239, 0x10010, v237
	ds_read_b128 v[202:205], v239
	ds_read_b128 v[206:209], v239 offset:2048
	ds_read_b128 v[210:213], v239 offset:4096
	ds_read_b128 v[214:217], v239 offset:6144
	v_add_u32_e32 v238, 0x10010, v236
	ds_read_b128 v[218:221], v238
	ds_read_b128 v[178:181], v238 offset:2048
	ds_read_b128 v[222:225], v238 offset:4096
	ds_read_b128 v[226:229], v238 offset:6144
	s_waitcnt lgkmcnt(3)
	v_mfma_f32_16x16x32_bf16 v[0:3], v[202:205], v[218:221], v[0:3]
	v_mfma_f32_16x16x32_bf16 v[32:35], v[206:209], v[218:221], v[32:35]
	v_mfma_f32_16x16x32_bf16 v[64:67], v[210:213], v[218:221], v[64:67]
	v_mfma_f32_16x16x32_bf16 v[96:99], v[214:217], v[218:221], v[96:99]
	s_waitcnt lgkmcnt(2)
	v_mfma_f32_16x16x32_bf16 v[4:7], v[202:205], v[178:181], v[4:7]
	v_mfma_f32_16x16x32_bf16 v[36:39], v[206:209], v[178:181], v[36:39]
	v_mfma_f32_16x16x32_bf16 v[68:71], v[210:213], v[178:181], v[68:71]
	v_mfma_f32_16x16x32_bf16 v[100:103], v[214:217], v[178:181], v[100:103]
	s_waitcnt lgkmcnt(1)
	v_mfma_f32_16x16x32_bf16 v[8:11], v[202:205], v[222:225], v[8:11]
	v_mfma_f32_16x16x32_bf16 v[40:43], v[206:209], v[222:225], v[40:43]
	v_mfma_f32_16x16x32_bf16 v[72:75], v[210:213], v[222:225], v[72:75]
	v_mfma_f32_16x16x32_bf16 v[104:107], v[214:217], v[222:225], v[104:107]
	s_waitcnt lgkmcnt(0)
	v_mfma_f32_16x16x32_bf16 v[12:15], v[202:205], v[226:229], v[12:15]
	v_mfma_f32_16x16x32_bf16 v[44:47], v[206:209], v[226:229], v[44:47]
	v_mfma_f32_16x16x32_bf16 v[76:79], v[210:213], v[226:229], v[76:79]
	v_mfma_f32_16x16x32_bf16 v[108:111], v[214:217], v[226:229], v[108:111]
	ds_read_b128 v[218:221], v238 offset:8192
	ds_read_b128 v[178:181], v238 offset:10240
	ds_read_b128 v[222:225], v238 offset:12288
	ds_read_b128 v[226:229], v238 offset:14336
	s_waitcnt lgkmcnt(3)
	v_mfma_f32_16x16x32_bf16 v[16:19], v[202:205], v[218:221], v[16:19]
	v_mfma_f32_16x16x32_bf16 v[48:51], v[206:209], v[218:221], v[48:51]
	v_mfma_f32_16x16x32_bf16 v[80:83], v[210:213], v[218:221], v[80:83]
	v_mfma_f32_16x16x32_bf16 v[112:115], v[214:217], v[218:221], v[112:115]
	s_waitcnt lgkmcnt(2)
	v_mfma_f32_16x16x32_bf16 v[20:23], v[202:205], v[178:181], v[20:23]
	v_mfma_f32_16x16x32_bf16 v[52:55], v[206:209], v[178:181], v[52:55]
	v_mfma_f32_16x16x32_bf16 v[84:87], v[210:213], v[178:181], v[84:87]
	v_mfma_f32_16x16x32_bf16 v[116:119], v[214:217], v[178:181], v[116:119]
	s_waitcnt lgkmcnt(1)
	v_mfma_f32_16x16x32_bf16 v[24:27], v[202:205], v[222:225], v[24:27]
	v_mfma_f32_16x16x32_bf16 v[56:59], v[206:209], v[222:225], v[56:59]
	v_mfma_f32_16x16x32_bf16 v[88:91], v[210:213], v[222:225], v[88:91]
	v_mfma_f32_16x16x32_bf16 v[120:123], v[214:217], v[222:225], v[120:123]
	s_waitcnt lgkmcnt(0)
	v_mfma_f32_16x16x32_bf16 v[28:31], v[202:205], v[226:229], v[28:31]
	v_mfma_f32_16x16x32_bf16 v[60:63], v[206:209], v[226:229], v[60:63]
	v_mfma_f32_16x16x32_bf16 v[92:95], v[210:213], v[226:229], v[92:95]
	v_mfma_f32_16x16x32_bf16 v[124:127], v[214:217], v[226:229], v[124:127]
	v_xor_b32_e32 v239, 64, v237
	v_add_u32_e32 v239, 0x10010, v239
	ds_read_b128 v[202:205], v239
	ds_read_b128 v[206:209], v239 offset:2048
	ds_read_b128 v[210:213], v239 offset:4096
	ds_read_b128 v[214:217], v239 offset:6144
	v_xor_b32_e32 v238, 64, v236
	v_add_u32_e32 v238, 0x10010, v238
	ds_read_b128 v[218:221], v238
	ds_read_b128 v[178:181], v238 offset:2048
	ds_read_b128 v[222:225], v238 offset:4096
	ds_read_b128 v[226:229], v238 offset:6144
	s_waitcnt lgkmcnt(3)
	v_mfma_f32_16x16x32_bf16 v[0:3], v[202:205], v[218:221], v[0:3]
	v_mfma_f32_16x16x32_bf16 v[32:35], v[206:209], v[218:221], v[32:35]
	v_mfma_f32_16x16x32_bf16 v[64:67], v[210:213], v[218:221], v[64:67]
	v_mfma_f32_16x16x32_bf16 v[96:99], v[214:217], v[218:221], v[96:99]
	s_waitcnt lgkmcnt(2)
	v_mfma_f32_16x16x32_bf16 v[4:7], v[202:205], v[178:181], v[4:7]
	v_mfma_f32_16x16x32_bf16 v[36:39], v[206:209], v[178:181], v[36:39]
	v_mfma_f32_16x16x32_bf16 v[68:71], v[210:213], v[178:181], v[68:71]
	v_mfma_f32_16x16x32_bf16 v[100:103], v[214:217], v[178:181], v[100:103]
	s_waitcnt lgkmcnt(1)
	v_mfma_f32_16x16x32_bf16 v[8:11], v[202:205], v[222:225], v[8:11]
	v_mfma_f32_16x16x32_bf16 v[40:43], v[206:209], v[222:225], v[40:43]
	v_mfma_f32_16x16x32_bf16 v[72:75], v[210:213], v[222:225], v[72:75]
	v_mfma_f32_16x16x32_bf16 v[104:107], v[214:217], v[222:225], v[104:107]
	s_waitcnt lgkmcnt(0)
	v_mfma_f32_16x16x32_bf16 v[12:15], v[202:205], v[226:229], v[12:15]
	v_mfma_f32_16x16x32_bf16 v[44:47], v[206:209], v[226:229], v[44:47]
	v_mfma_f32_16x16x32_bf16 v[76:79], v[210:213], v[226:229], v[76:79]
	v_mfma_f32_16x16x32_bf16 v[108:111], v[214:217], v[226:229], v[108:111]
	ds_read_b128 v[218:221], v238 offset:8192
	ds_read_b128 v[178:181], v238 offset:10240
	ds_read_b128 v[222:225], v238 offset:12288
	ds_read_b128 v[226:229], v238 offset:14336
	s_waitcnt lgkmcnt(3)
	v_mfma_f32_16x16x32_bf16 v[16:19], v[202:205], v[218:221], v[16:19]
	v_mfma_f32_16x16x32_bf16 v[48:51], v[206:209], v[218:221], v[48:51]
	v_mfma_f32_16x16x32_bf16 v[80:83], v[210:213], v[218:221], v[80:83]
	v_mfma_f32_16x16x32_bf16 v[112:115], v[214:217], v[218:221], v[112:115]
	s_waitcnt lgkmcnt(2)
	v_mfma_f32_16x16x32_bf16 v[20:23], v[202:205], v[178:181], v[20:23]
	v_mfma_f32_16x16x32_bf16 v[52:55], v[206:209], v[178:181], v[52:55]
	v_mfma_f32_16x16x32_bf16 v[84:87], v[210:213], v[178:181], v[84:87]
	v_mfma_f32_16x16x32_bf16 v[116:119], v[214:217], v[178:181], v[116:119]
	s_waitcnt lgkmcnt(1)
	v_mfma_f32_16x16x32_bf16 v[24:27], v[202:205], v[222:225], v[24:27]
	v_mfma_f32_16x16x32_bf16 v[56:59], v[206:209], v[222:225], v[56:59]
	v_mfma_f32_16x16x32_bf16 v[88:91], v[210:213], v[222:225], v[88:91]
	v_mfma_f32_16x16x32_bf16 v[120:123], v[214:217], v[222:225], v[120:123]
	s_waitcnt lgkmcnt(0)
	v_mfma_f32_16x16x32_bf16 v[28:31], v[202:205], v[226:229], v[28:31]
	v_mfma_f32_16x16x32_bf16 v[60:63], v[206:209], v[226:229], v[60:63]
	v_mfma_f32_16x16x32_bf16 v[92:95], v[210:213], v[226:229], v[92:95]
	v_mfma_f32_16x16x32_bf16 v[124:127], v[214:217], v[226:229], v[124:127]
	s_and_saveexec_b64 s[14:15], s[6:7]
	s_cbranch_execz .LBB0_698
	v_mul_f32_e32 v134, 0x4b800000, v133
	v_cmp_gt_f32_e32 vcc, s28, v133
	s_nop 1
	v_cndmask_b32_e32 v133, v133, v134, vcc
	v_rsq_f32_e32 v133, v133
	s_nop 0
	v_mul_f32_e32 v134, 0x45800000, v133
	v_cndmask_b32_e32 v133, v133, v134, vcc
	ds_write_b32 v162, v133
	s_branch .LBB0_698
